# prologue channel-DFT weight fold moved from per-MAC LDS-gather VALU loop to the f32 matrix core (v_mfma_f32_16x16x4_f32, f32 operands/accumulate, same k-ordered sums)
# speedup vs baseline: 1.0514x; 1.0187x over previous
; __device__ __forceinline__ unsigned pk2(float lo, float hi) { return f2bf(lo) | (f2bf(hi) << 16); }
; __device__ __forceinline__ void ph_prologue(const Params& p_, unsigned char* lds) {
;     ...
;     { float* Wl = (float*)lds; float* tr = Wl + 128 * 65; bf16* Wcs = (bf16*)(p.ws + WS_WCS);
;       for (int t2 = G - 1 - bid; t2 < 256; t2 += G) {
;           const int t = t2 >> 1, ch = t2 & 1, l = t >> 6, pq = (t >> 5) & 1, g = (t >> 3) & 3, n0 = (t & 7) * 64;
; #pragma unroll
;           for (int i = 0; i < 4; ++i) { const int m = (tid >> 4) + 32 * i, nn = (tid & 15) * 4;
;               const f32x4 v = *(const f32x4*)(p.w_fft + ((size_t)l * DG + g * 128 + m) * DG + n0 + nn);
;               Wl[m * 65 + nn] = v[0]; Wl[m * 65 + nn + 1] = v[1]; Wl[m * 65 + nn + 2] = v[2]; Wl[m * 65 + nn + 3] = v[3]; }
;           if (tid < 128) tr[tid] = pq ? sinpif((float)tid * (1.f / 64.f)) : cospif((float)tid * (1.f / 64.f));
;           __syncthreads();
;           const int nn = tid >> 3, cc = ch * 64 + (tid & 7) * 8; float acc[8];
; #pragma unroll
;           for (int i = 0; i < 8; ++i) acc[i] = 0.f;
; #pragma unroll 4
;           for (int m = 0; m < 128; ++m) { const float w = Wl[m * 65 + nn];
; #pragma unroll
;               for (int i = 0; i < 8; ++i) acc[i] += tr[((cc + i) * m) & 127] * w; }
;           const float nrm = 0.0013810679320049757f;
;           u32x4 o0;
;           o0.x = pk2(acc[0] * nrm, acc[1] * nrm); o0.y = pk2(acc[2] * nrm, acc[3] * nrm); o0.z = pk2(acc[4] * nrm, acc[5] * nrm); o0.w = pk2(acc[6] * nrm, acc[7] * nrm);
;           *(u32x4*)(Wcs + ((size_t)l * 1024 + pq * 512 + n0 + nn) * DG + g * 128 + cc) = o0;
.LBB0_42:
	s_ashr_i32 s18, s29, 7
	s_lshl_b32 s4, s29, 5
	s_ashr_i32 s19, s18, 31
	s_lshl_b32 s16, s29, 3
	s_and_b32 s41, s4, 0x1c0
	s_lshl_b64 s[4:5], s[18:19], 9
	s_and_b32 s40, s16, 0x180
	s_or_b32 s4, s4, s40
	s_lshl_b32 s16, s41, 2
	v_lshl_add_u64 v[18:19], s[4:5], 0, v[2:3]
	v_lshl_add_u64 v[26:27], v[6:7], 0, s[16:17]
	v_lshlrev_b64 v[18:19], 11, v[18:19]
	v_lshl_add_u64 v[50:51], v[26:27], 0, v[18:19]
	v_lshl_add_u64 v[18:19], s[4:5], 0, v[10:11]
	v_lshlrev_b64 v[18:19], 11, v[18:19]
	v_lshl_add_u64 v[52:53], v[26:27], 0, v[18:19]
	global_load_dwordx4 v[18:21], v[50:51], off
	global_load_dwordx4 v[22:25], v[52:53], off
	v_lshl_add_u64 v[50:51], s[4:5], 0, v[12:13]
	v_lshlrev_b64 v[50:51], 11, v[50:51]
	v_lshl_add_u64 v[50:51], v[26:27], 0, v[50:51]
	v_lshl_add_u64 v[54:55], s[4:5], 0, v[14:15]
	global_load_dwordx4 v[50:53], v[50:51], off
	v_lshlrev_b64 v[54:55], 11, v[54:55]
	v_lshl_add_u64 v[26:27], v[26:27], 0, v[54:55]
	global_load_dwordx4 v[54:57], v[26:27], off
	s_bfe_u32 s16, s29, 0x10006
	s_waitcnt vmcnt(3)
	ds_write2_b32 v42, v18, v19 offset1:1
	ds_write2_b32 v42, v20, v21 offset0:2 offset1:3
	s_waitcnt vmcnt(2)
	ds_write2_b32 v43, v22, v23 offset1:1
	ds_write2_b32 v44, v24, v25 offset1:1
	s_waitcnt vmcnt(1)
	ds_write2_b32 v45, v50, v51 offset1:1
	ds_write2_b32 v46, v52, v53 offset1:1
	s_waitcnt vmcnt(0)
	ds_write2_b32 v47, v54, v55 offset1:1
	ds_write2_b32 v48, v56, v57 offset1:1
	s_and_saveexec_b64 s[36:37], vcc
	s_cmp_eq_u32 s16, 0
	s_cselect_b64 s[4:5], -1, 0
	v_cndmask_b32_e64 v4, v17, v28, s[4:5]
	ds_write_b32 v29, v4 offset:33280
	s_or_b64 exec, exec, s[36:37]
	v_and_b32_e32 v150, 63, v16
	v_lshrrev_b32_e32 v151, 6, v16
	v_and_b32_e32 v152, 15, v150
	v_lshrrev_b32_e32 v153, 4, v150
	v_and_b32_e32 v154, 3, v151
	v_lshrrev_b32_e32 v155, 2, v151
	s_and_b32 s72, s29, 1
	s_lshl_b32 s72, s72, 6
	v_lshl_add_u32 v156, v154, 4, v152
	v_add_u32_e32 v156, s72, v156
	v_mul_u32_u24_e32 v157, v156, v153
	v_lshlrev_b32_e32 v157, 2, v157
	v_and_b32_e32 v157, 0x1fc, v157
	v_lshlrev_b32_e32 v158, 4, v156
	v_and_b32_e32 v158, 0x1fc, v158
	v_mul_u32_u24_e32 v159, 0x104, v153
	v_lshl_add_u32 v160, v155, 5, v152
	v_lshl_add_u32 v159, v160, 2, v159
	v_mov_b32_e32 v162, 0
	v_mov_b32_e32 v163, 0
	v_mov_b32_e32 v164, 0
	v_mov_b32_e32 v165, 0
	v_mov_b32_e32 v166, 0
	v_mov_b32_e32 v167, 0
	v_mov_b32_e32 v168, 0
	v_mov_b32_e32 v169, 0
	s_waitcnt lgkmcnt(0)
	s_barrier
	ds_read_b32 v170, v157 offset:33280
	ds_read_b32 v171, v159 offset:0
	ds_read_b32 v172, v159 offset:64
	v_add_u32_e32 v157, v157, v158
	v_and_b32_e32 v157, 0x1fc, v157
	ds_read_b32 v173, v157 offset:33280
	ds_read_b32 v174, v159 offset:1040
	ds_read_b32 v175, v159 offset:1104
	v_add_u32_e32 v157, v157, v158
	v_and_b32_e32 v157, 0x1fc, v157
	s_waitcnt lgkmcnt(3)
	v_mfma_f32_16x16x4_f32 v[162:165], v170, v171, v[162:165]
	v_mfma_f32_16x16x4_f32 v[166:169], v170, v172, v[166:169]
	ds_read_b32 v170, v157 offset:33280
	ds_read_b32 v171, v159 offset:2080
	ds_read_b32 v172, v159 offset:2144
	v_add_u32_e32 v157, v157, v158
	v_and_b32_e32 v157, 0x1fc, v157
	s_waitcnt lgkmcnt(3)
	v_mfma_f32_16x16x4_f32 v[162:165], v173, v174, v[162:165]
	v_mfma_f32_16x16x4_f32 v[166:169], v173, v175, v[166:169]
	ds_read_b32 v173, v157 offset:33280
	ds_read_b32 v174, v159 offset:3120
	ds_read_b32 v175, v159 offset:3184
	v_add_u32_e32 v157, v157, v158
	v_and_b32_e32 v157, 0x1fc, v157
	s_waitcnt lgkmcnt(3)
	v_mfma_f32_16x16x4_f32 v[162:165], v170, v171, v[162:165]
	v_mfma_f32_16x16x4_f32 v[166:169], v170, v172, v[166:169]
	ds_read_b32 v170, v157 offset:33280
	ds_read_b32 v171, v159 offset:4160
	ds_read_b32 v172, v159 offset:4224
	v_add_u32_e32 v157, v157, v158
	v_and_b32_e32 v157, 0x1fc, v157
	s_waitcnt lgkmcnt(3)
	v_mfma_f32_16x16x4_f32 v[162:165], v173, v174, v[162:165]
	v_mfma_f32_16x16x4_f32 v[166:169], v173, v175, v[166:169]
	ds_read_b32 v173, v157 offset:33280
	ds_read_b32 v174, v159 offset:5200
	ds_read_b32 v175, v159 offset:5264
	v_add_u32_e32 v157, v157, v158
	v_and_b32_e32 v157, 0x1fc, v157
	s_waitcnt lgkmcnt(3)
	v_mfma_f32_16x16x4_f32 v[162:165], v170, v171, v[162:165]
	v_mfma_f32_16x16x4_f32 v[166:169], v170, v172, v[166:169]
	ds_read_b32 v170, v157 offset:33280
	ds_read_b32 v171, v159 offset:6240
	ds_read_b32 v172, v159 offset:6304
	v_add_u32_e32 v157, v157, v158
	v_and_b32_e32 v157, 0x1fc, v157
	s_waitcnt lgkmcnt(3)
	v_mfma_f32_16x16x4_f32 v[162:165], v173, v174, v[162:165]
	v_mfma_f32_16x16x4_f32 v[166:169], v173, v175, v[166:169]
	ds_read_b32 v173, v157 offset:33280
	ds_read_b32 v174, v159 offset:7280
	ds_read_b32 v175, v159 offset:7344
	v_add_u32_e32 v157, v157, v158
	v_and_b32_e32 v157, 0x1fc, v157
	s_waitcnt lgkmcnt(3)
	v_mfma_f32_16x16x4_f32 v[162:165], v170, v171, v[162:165]
	v_mfma_f32_16x16x4_f32 v[166:169], v170, v172, v[166:169]
	ds_read_b32 v170, v157 offset:33280
	ds_read_b32 v171, v159 offset:8320
	ds_read_b32 v172, v159 offset:8384
	v_add_u32_e32 v157, v157, v158
	v_and_b32_e32 v157, 0x1fc, v157
	s_waitcnt lgkmcnt(3)
	v_mfma_f32_16x16x4_f32 v[162:165], v173, v174, v[162:165]
	v_mfma_f32_16x16x4_f32 v[166:169], v173, v175, v[166:169]
	ds_read_b32 v173, v157 offset:33280
	ds_read_b32 v174, v159 offset:9360
	ds_read_b32 v175, v159 offset:9424
	v_add_u32_e32 v157, v157, v158
	v_and_b32_e32 v157, 0x1fc, v157
	s_waitcnt lgkmcnt(3)
	v_mfma_f32_16x16x4_f32 v[162:165], v170, v171, v[162:165]
	v_mfma_f32_16x16x4_f32 v[166:169], v170, v172, v[166:169]
	ds_read_b32 v170, v157 offset:33280
	ds_read_b32 v171, v159 offset:10400
	ds_read_b32 v172, v159 offset:10464
	v_add_u32_e32 v157, v157, v158
	v_and_b32_e32 v157, 0x1fc, v157
	s_waitcnt lgkmcnt(3)
; __device__ __forceinline__ void ph_prologue(const Params& p_, unsigned char* lds) {
;     ...
; #pragma unroll 4
;           for (int m = 0; m < 128; ++m) { const float w = Wl[m * 65 + nn];
; #pragma unroll
;               for (int i = 0; i < 8; ++i) acc[i] += tr[((cc + i) * m) & 127] * w; }
	v_mfma_f32_16x16x4_f32 v[162:165], v173, v174, v[162:165]
	v_mfma_f32_16x16x4_f32 v[166:169], v173, v175, v[166:169]
	ds_read_b32 v173, v157 offset:33280
	ds_read_b32 v174, v159 offset:11440
	ds_read_b32 v175, v159 offset:11504
	v_add_u32_e32 v157, v157, v158
	v_and_b32_e32 v157, 0x1fc, v157
	s_waitcnt lgkmcnt(3)
	v_mfma_f32_16x16x4_f32 v[162:165], v170, v171, v[162:165]
	v_mfma_f32_16x16x4_f32 v[166:169], v170, v172, v[166:169]
	ds_read_b32 v170, v157 offset:33280
	ds_read_b32 v171, v159 offset:12480
	ds_read_b32 v172, v159 offset:12544
	v_add_u32_e32 v157, v157, v158
	v_and_b32_e32 v157, 0x1fc, v157
	s_waitcnt lgkmcnt(3)
	v_mfma_f32_16x16x4_f32 v[162:165], v173, v174, v[162:165]
	v_mfma_f32_16x16x4_f32 v[166:169], v173, v175, v[166:169]
	ds_read_b32 v173, v157 offset:33280
	ds_read_b32 v174, v159 offset:13520
	ds_read_b32 v175, v159 offset:13584
	v_add_u32_e32 v157, v157, v158
	v_and_b32_e32 v157, 0x1fc, v157
	s_waitcnt lgkmcnt(3)
	v_mfma_f32_16x16x4_f32 v[162:165], v170, v171, v[162:165]
	v_mfma_f32_16x16x4_f32 v[166:169], v170, v172, v[166:169]
	ds_read_b32 v170, v157 offset:33280
	ds_read_b32 v171, v159 offset:14560
	ds_read_b32 v172, v159 offset:14624
	v_add_u32_e32 v157, v157, v158
	v_and_b32_e32 v157, 0x1fc, v157
	s_waitcnt lgkmcnt(3)
	v_mfma_f32_16x16x4_f32 v[162:165], v173, v174, v[162:165]
	v_mfma_f32_16x16x4_f32 v[166:169], v173, v175, v[166:169]
	ds_read_b32 v173, v157 offset:33280
	ds_read_b32 v174, v159 offset:15600
	ds_read_b32 v175, v159 offset:15664
	v_add_u32_e32 v157, v157, v158
	v_and_b32_e32 v157, 0x1fc, v157
	s_waitcnt lgkmcnt(3)
	v_mfma_f32_16x16x4_f32 v[162:165], v170, v171, v[162:165]
	v_mfma_f32_16x16x4_f32 v[166:169], v170, v172, v[166:169]
	ds_read_b32 v170, v157 offset:33280
	ds_read_b32 v171, v159 offset:16640
	ds_read_b32 v172, v159 offset:16704
	v_add_u32_e32 v157, v157, v158
	v_and_b32_e32 v157, 0x1fc, v157
	s_waitcnt lgkmcnt(3)
	v_mfma_f32_16x16x4_f32 v[162:165], v173, v174, v[162:165]
	v_mfma_f32_16x16x4_f32 v[166:169], v173, v175, v[166:169]
	ds_read_b32 v173, v157 offset:33280
	ds_read_b32 v174, v159 offset:17680
	ds_read_b32 v175, v159 offset:17744
	v_add_u32_e32 v157, v157, v158
	v_and_b32_e32 v157, 0x1fc, v157
	s_waitcnt lgkmcnt(3)
	v_mfma_f32_16x16x4_f32 v[162:165], v170, v171, v[162:165]
	v_mfma_f32_16x16x4_f32 v[166:169], v170, v172, v[166:169]
	ds_read_b32 v170, v157 offset:33280
	ds_read_b32 v171, v159 offset:18720
	ds_read_b32 v172, v159 offset:18784
	v_add_u32_e32 v157, v157, v158
	v_and_b32_e32 v157, 0x1fc, v157
	s_waitcnt lgkmcnt(3)
	v_mfma_f32_16x16x4_f32 v[162:165], v173, v174, v[162:165]
	v_mfma_f32_16x16x4_f32 v[166:169], v173, v175, v[166:169]
	ds_read_b32 v173, v157 offset:33280
	ds_read_b32 v174, v159 offset:19760
	ds_read_b32 v175, v159 offset:19824
	v_add_u32_e32 v157, v157, v158
	v_and_b32_e32 v157, 0x1fc, v157
	s_waitcnt lgkmcnt(3)
	v_mfma_f32_16x16x4_f32 v[162:165], v170, v171, v[162:165]
	v_mfma_f32_16x16x4_f32 v[166:169], v170, v172, v[166:169]
	ds_read_b32 v170, v157 offset:33280
	ds_read_b32 v171, v159 offset:20800
	ds_read_b32 v172, v159 offset:20864
	v_add_u32_e32 v157, v157, v158
	v_and_b32_e32 v157, 0x1fc, v157
	s_waitcnt lgkmcnt(3)
	v_mfma_f32_16x16x4_f32 v[162:165], v173, v174, v[162:165]
	v_mfma_f32_16x16x4_f32 v[166:169], v173, v175, v[166:169]
	ds_read_b32 v173, v157 offset:33280
	ds_read_b32 v174, v159 offset:21840
	ds_read_b32 v175, v159 offset:21904
	v_add_u32_e32 v157, v157, v158
	v_and_b32_e32 v157, 0x1fc, v157
	s_waitcnt lgkmcnt(3)
	v_mfma_f32_16x16x4_f32 v[162:165], v170, v171, v[162:165]
	v_mfma_f32_16x16x4_f32 v[166:169], v170, v172, v[166:169]
	ds_read_b32 v170, v157 offset:33280
	ds_read_b32 v171, v159 offset:22880
	ds_read_b32 v172, v159 offset:22944
	v_add_u32_e32 v157, v157, v158
	v_and_b32_e32 v157, 0x1fc, v157
	s_waitcnt lgkmcnt(3)
; __device__ __forceinline__ unsigned pk2(float lo, float hi) { return f2bf(lo) | (f2bf(hi) << 16); }
; __device__ __forceinline__ void ph_prologue(const Params& p_, unsigned char* lds) {
;     ...
;           for (int m = 0; m < 128; ++m) { const float w = Wl[m * 65 + nn];
; #pragma unroll
;               for (int i = 0; i < 8; ++i) acc[i] += tr[((cc + i) * m) & 127] * w; }
;           const float nrm = 0.0013810679320049757f;
;           u32x4 o0;
;           o0.x = pk2(acc[0] * nrm, acc[1] * nrm); o0.y = pk2(acc[2] * nrm, acc[3] * nrm); o0.z = pk2(acc[4] * nrm, acc[5] * nrm); o0.w = pk2(acc[6] * nrm, acc[7] * nrm);
;           *(u32x4*)(Wcs + ((size_t)l * 1024 + pq * 512 + n0 + nn) * DG + g * 128 + cc) = o0;
;           __syncthreads();
	v_mfma_f32_16x16x4_f32 v[162:165], v173, v174, v[162:165]
	v_mfma_f32_16x16x4_f32 v[166:169], v173, v175, v[166:169]
	ds_read_b32 v173, v157 offset:33280
	ds_read_b32 v174, v159 offset:23920
	ds_read_b32 v175, v159 offset:23984
	v_add_u32_e32 v157, v157, v158
	v_and_b32_e32 v157, 0x1fc, v157
	s_waitcnt lgkmcnt(3)
	v_mfma_f32_16x16x4_f32 v[162:165], v170, v171, v[162:165]
	v_mfma_f32_16x16x4_f32 v[166:169], v170, v172, v[166:169]
	ds_read_b32 v170, v157 offset:33280
	ds_read_b32 v171, v159 offset:24960
	ds_read_b32 v172, v159 offset:25024
	v_add_u32_e32 v157, v157, v158
	v_and_b32_e32 v157, 0x1fc, v157
	s_waitcnt lgkmcnt(3)
	v_mfma_f32_16x16x4_f32 v[162:165], v173, v174, v[162:165]
	v_mfma_f32_16x16x4_f32 v[166:169], v173, v175, v[166:169]
	ds_read_b32 v173, v157 offset:33280
	ds_read_b32 v174, v159 offset:26000
	ds_read_b32 v175, v159 offset:26064
	v_add_u32_e32 v157, v157, v158
	v_and_b32_e32 v157, 0x1fc, v157
	s_waitcnt lgkmcnt(3)
	v_mfma_f32_16x16x4_f32 v[162:165], v170, v171, v[162:165]
	v_mfma_f32_16x16x4_f32 v[166:169], v170, v172, v[166:169]
	ds_read_b32 v170, v157 offset:33280
	ds_read_b32 v171, v159 offset:27040
	ds_read_b32 v172, v159 offset:27104
	v_add_u32_e32 v157, v157, v158
	v_and_b32_e32 v157, 0x1fc, v157
	s_waitcnt lgkmcnt(3)
	v_mfma_f32_16x16x4_f32 v[162:165], v173, v174, v[162:165]
	v_mfma_f32_16x16x4_f32 v[166:169], v173, v175, v[166:169]
	ds_read_b32 v173, v157 offset:33280
	ds_read_b32 v174, v159 offset:28080
	ds_read_b32 v175, v159 offset:28144
	v_add_u32_e32 v157, v157, v158
	v_and_b32_e32 v157, 0x1fc, v157
	s_waitcnt lgkmcnt(3)
	v_mfma_f32_16x16x4_f32 v[162:165], v170, v171, v[162:165]
	v_mfma_f32_16x16x4_f32 v[166:169], v170, v172, v[166:169]
	ds_read_b32 v170, v157 offset:33280
	ds_read_b32 v171, v159 offset:29120
	ds_read_b32 v172, v159 offset:29184
	v_add_u32_e32 v157, v157, v158
	v_and_b32_e32 v157, 0x1fc, v157
	s_waitcnt lgkmcnt(3)
	v_mfma_f32_16x16x4_f32 v[162:165], v173, v174, v[162:165]
	v_mfma_f32_16x16x4_f32 v[166:169], v173, v175, v[166:169]
	ds_read_b32 v173, v157 offset:33280
	ds_read_b32 v174, v159 offset:30160
	ds_read_b32 v175, v159 offset:30224
	v_add_u32_e32 v157, v157, v158
	v_and_b32_e32 v157, 0x1fc, v157
	s_waitcnt lgkmcnt(3)
	v_mfma_f32_16x16x4_f32 v[162:165], v170, v171, v[162:165]
	v_mfma_f32_16x16x4_f32 v[166:169], v170, v172, v[166:169]
	ds_read_b32 v170, v157 offset:33280
	ds_read_b32 v171, v159 offset:31200
	ds_read_b32 v172, v159 offset:31264
	v_add_u32_e32 v157, v157, v158
	v_and_b32_e32 v157, 0x1fc, v157
	s_waitcnt lgkmcnt(3)
	v_mfma_f32_16x16x4_f32 v[162:165], v173, v174, v[162:165]
	v_mfma_f32_16x16x4_f32 v[166:169], v173, v175, v[166:169]
	ds_read_b32 v173, v157 offset:33280
	ds_read_b32 v174, v159 offset:32240
	ds_read_b32 v175, v159 offset:32304
	v_add_u32_e32 v157, v157, v158
	v_and_b32_e32 v157, 0x1fc, v157
	s_waitcnt lgkmcnt(3)
	v_mfma_f32_16x16x4_f32 v[162:165], v170, v171, v[162:165]
	v_mfma_f32_16x16x4_f32 v[166:169], v170, v172, v[166:169]
	s_waitcnt lgkmcnt(0)
	v_mfma_f32_16x16x4_f32 v[162:165], v173, v174, v[162:165]
	v_mfma_f32_16x16x4_f32 v[166:169], v173, v175, v[166:169]
	s_lshl_b32 s73, s16, 9
	s_or_b32 s73, s41, s73
	s_lshl_b32 s74, s18, 10
	s_or_b32 s74, s74, s73
	s_add_i32 s76, s40, s72
	s_lshl_b32 s76, s76, 1
	v_add_u32_e32 v180, s74, v160
	v_lshlrev_b32_e32 v180, 10, v180
	v_lshlrev_b32_e32 v181, 3, v153
	v_lshl_add_u32 v181, v154, 5, v181
	v_add3_u32 v180, v180, v181, s76
	v_add_u32_e32 v182, 0x4000, v180
	s_nop 3
	v_mul_f32_e32 v162, s6, v162
	v_mul_f32_e32 v163, s6, v163
	v_mul_f32_e32 v164, s6, v164
	v_mul_f32_e32 v165, s6, v165
	v_mul_f32_e32 v166, s6, v166
	v_mul_f32_e32 v167, s6, v167
	v_mul_f32_e32 v168, s6, v168
	v_mul_f32_e32 v169, s6, v169
	v_cvt_pk_bf16_f32 v176, v162, v163
	v_cvt_pk_bf16_f32 v177, v164, v165
	v_cvt_pk_bf16_f32 v178, v166, v167
	v_cvt_pk_bf16_f32 v179, v168, v169
	s_add_i32 s29, s29, s66
	s_add_i32 s7, s7, s30
	s_cmpk_gt_i32 s29, 0xff
	global_store_dwordx2 v180, v[176:177], s[8:9]
	global_store_dwordx2 v182, v[178:179], s[8:9]
	s_barrier
	s_cbranch_scc0 .LBB0_42
